# raised wave priority for waves 4-7 also in the GEMM phases (2 3 5 7 9 11 16 18 19 21)
# baseline (speedup 1.0000x reference)
.LBB0_295:
	s_cmp_gt_i32 s44, 2
	s_cselect_b64 s[2:3], -1, 0
	s_cmp_lt_i32 s45, 3
	s_cselect_b64 s[4:5], -1, 0
	s_or_b64 s[2:3], s[2:3], s[4:5]
	s_and_b64 vcc, exec, s[2:3]
	s_cbranch_vccnz .LBB0_865
	s_cmp_lt_u32 s70, 256
	s_cbranch_scc1 .Lprio_skip_2
	s_setprio 3
.Lprio_skip_2:
	s_and_b32 s2, s42, 7
	s_cmp_lg_u32 s2, 0
	s_mov_b32 s6, s22
	s_cbranch_scc1 .LBB0_298
	s_and_b32 s2, s22, 7
	s_ashr_i32 s3, s42, 3
	s_mul_i32 s2, s3, s2
	s_ashr_i32 s3, s22, 3
	s_add_i32 s6, s2, s3

.LBB0_811:
	s_setprio 0
	s_cmp_lt_i32 s45, 4
	s_cbranch_scc1 .LBB0_865
	s_waitcnt vmcnt(0) lgkmcnt(0)
	s_barrier
	v_mbcnt_hi_u32_b32 v0, -1, v210
	v_cmp_eq_u32_e32 vcc, 0, v0
	s_and_b64 s[4:5], s[46:47], vcc
	s_and_saveexec_b64 s[2:3], s[4:5]
	s_cbranch_execz .Lfb2_join
	v_mov_b32_e32 v0, 0x24400
	ds_read_b32 v1, v0
	ds_read_b32 v2, v0 offset:4
	ds_read_b32 v3, v0 offset:8
	s_waitcnt lgkmcnt(0)
	v_readfirstlane_b32 s4, v1
	v_readfirstlane_b32 s5, v2
	v_readfirstlane_b32 s6, v3
	s_add_u32 s7, s6, 1
	v_mov_b32_e32 v4, s7
	ds_write_b32 v0, v4 offset:8
	s_mul_i32 s8, s7, s4
	s_mul_i32 s9, s7, s5
	s_lshl_b32 s10, s23, 7
	s_add_u32 s10, s10, 0x3600
	v_mov_b32_e32 v1, s10
	v_mov_b32_e32 v2, 1
	global_atomic_add v3, v1, v2, s[40:41] sc0
	s_waitcnt vmcnt(0)
	v_readfirstlane_b32 s11, v3
	s_add_u32 s11, s11, 1
	v_mov_b32_e32 v1, 0x3e00
	s_cmp_lg_u32 s11, s8
	s_cbranch_scc1 .Lfb2_spin
	buffer_wbl2 sc1
	s_waitcnt vmcnt(0)
	global_atomic_add v1, v2, s[40:41]

.LBB0_865:
	s_cmp_gt_i32 s44, 3
	s_waitcnt lgkmcnt(0)
	s_cselect_b64 s[2:3], -1, 0
	s_cmp_lt_i32 s45, 4
	s_cselect_b64 s[4:5], -1, 0
	s_or_b64 s[2:3], s[2:3], s[4:5]
	s_and_b64 vcc, exec, s[2:3]
	s_cbranch_vccnz .LBB0_1194
	s_cmp_lt_u32 s70, 256
	s_cbranch_scc1 .Lprio_skip_3
	s_setprio 3

.Lmq3k_done:
.LBB0_1140:
	s_setprio 0
	s_cmp_lt_i32 s45, 5
	s_cbranch_scc1 .LBB0_1194
	s_waitcnt vmcnt(0) lgkmcnt(0)
	s_barrier
	v_mbcnt_hi_u32_b32 v0, -1, v210
	v_cmp_eq_u32_e32 vcc, 0, v0
	s_and_b64 s[4:5], s[46:47], vcc
	s_and_saveexec_b64 s[2:3], s[4:5]
	s_cbranch_execz .Lfb3_join
	v_mov_b32_e32 v0, 0x24400
	ds_read_b32 v1, v0
	ds_read_b32 v2, v0 offset:4
	ds_read_b32 v3, v0 offset:8
	s_waitcnt lgkmcnt(0)
	v_readfirstlane_b32 s4, v1
	v_readfirstlane_b32 s5, v2
	v_readfirstlane_b32 s6, v3
	s_add_u32 s7, s6, 1
	v_mov_b32_e32 v4, s7
	ds_write_b32 v0, v4 offset:8
	s_mul_i32 s8, s7, s4
	s_mul_i32 s9, s7, s5
	s_lshl_b32 s10, s23, 7
	s_add_u32 s10, s10, 0x3600
	v_mov_b32_e32 v1, s10
	v_mov_b32_e32 v2, 1
	global_atomic_add v3, v1, v2, s[40:41] sc0
	s_waitcnt vmcnt(0)
	v_readfirstlane_b32 s11, v3
	s_add_u32 s11, s11, 1
	v_mov_b32_e32 v1, 0x3e00
	s_cmp_lg_u32 s11, s8
	s_cbranch_scc1 .Lfb3_spin
	buffer_wbl2 sc1
	s_waitcnt vmcnt(0)
	global_atomic_add v1, v2, s[40:41]

.LBB0_1267:
	s_cmp_gt_i32 s44, 5
	s_cselect_b64 s[2:3], -1, 0
	s_cmp_lt_i32 s45, 6
	s_cselect_b64 s[4:5], -1, 0
	s_or_b64 s[2:3], s[2:3], s[4:5]
	s_and_b64 vcc, exec, s[2:3]
	s_cbranch_vccnz .LBB0_1397
	s_cmp_lt_u32 s70, 256
	s_cbranch_scc1 .Lprio_skip_5
	s_setprio 3

.LBB0_1343:
	s_setprio 0
	s_cmp_lt_i32 s45, 7
	s_cbranch_scc1 .LBB0_1397
	s_waitcnt vmcnt(0) lgkmcnt(0)
	s_barrier
	v_mbcnt_hi_u32_b32 v0, -1, v210
	v_cmp_eq_u32_e32 vcc, 0, v0
	s_and_b64 s[4:5], s[46:47], vcc
	s_and_saveexec_b64 s[2:3], s[4:5]
	s_cbranch_execz .Lfb5_join
	v_mov_b32_e32 v0, 0x24400
	ds_read_b32 v1, v0
	ds_read_b32 v2, v0 offset:4
	ds_read_b32 v3, v0 offset:8
	s_waitcnt lgkmcnt(0)
	v_readfirstlane_b32 s4, v1
	v_readfirstlane_b32 s5, v2
	v_readfirstlane_b32 s6, v3
	s_add_u32 s7, s6, 1
	v_mov_b32_e32 v4, s7
	ds_write_b32 v0, v4 offset:8
	s_mul_i32 s8, s7, s4
	s_mul_i32 s9, s7, s5
	s_lshl_b32 s10, s23, 7
	s_add_u32 s10, s10, 0x3600
	v_mov_b32_e32 v1, s10
	v_mov_b32_e32 v2, 1
	global_atomic_add v3, v1, v2, s[40:41] sc0
	s_waitcnt vmcnt(0)
	v_readfirstlane_b32 s11, v3
	s_add_u32 s11, s11, 1
	v_mov_b32_e32 v1, 0x3e00
	s_cmp_lg_u32 s11, s8
	s_cbranch_scc1 .Lfb5_spin
	buffer_wbl2 sc1
	s_waitcnt vmcnt(0)
	global_atomic_add v1, v2, s[40:41]

.LBB0_1457:
	s_cmp_gt_i32 s44, 7
	s_cselect_b64 s[2:3], -1, 0
	s_cmp_lt_i32 s45, 8
	s_cselect_b64 s[4:5], -1, 0
	s_or_b64 s[2:3], s[2:3], s[4:5]
	s_and_b64 vcc, exec, s[2:3]
	s_cbranch_vccnz .LBB0_2131
	s_cmp_lt_u32 s70, 256
	s_cbranch_scc1 .Lprio_skip_7
	s_setprio 3

.LBB0_2077:
	s_setprio 0
	s_cmp_lt_i32 s45, 9
	s_cbranch_scc1 .LBB0_2131
	s_waitcnt vmcnt(0) lgkmcnt(0)
	s_barrier
	v_mbcnt_hi_u32_b32 v0, -1, v210
	v_cmp_eq_u32_e32 vcc, 0, v0
	s_and_b64 s[4:5], s[46:47], vcc
	s_and_saveexec_b64 s[2:3], s[4:5]
	s_cbranch_execz .Lfb7_join
	v_mov_b32_e32 v0, 0x24400
	ds_read_b32 v1, v0
	ds_read_b32 v2, v0 offset:4
	ds_read_b32 v3, v0 offset:8
	s_waitcnt lgkmcnt(0)
	v_readfirstlane_b32 s4, v1
	v_readfirstlane_b32 s5, v2
	v_readfirstlane_b32 s6, v3
	s_add_u32 s7, s6, 1
	v_mov_b32_e32 v4, s7
	ds_write_b32 v0, v4 offset:8
	s_mul_i32 s8, s7, s4
	s_mul_i32 s9, s7, s5
	s_lshl_b32 s10, s23, 7
	s_add_u32 s10, s10, 0x3600
	v_mov_b32_e32 v1, s10
	v_mov_b32_e32 v2, 1
	global_atomic_add v3, v1, v2, s[40:41] sc0
	s_waitcnt vmcnt(0)
	v_readfirstlane_b32 s11, v3
	s_add_u32 s11, s11, 1
	v_mov_b32_e32 v1, 0x3e00
	s_cmp_lg_u32 s11, s8
	s_cbranch_scc1 .Lfb7_spin
	buffer_wbl2 sc1
	s_waitcnt vmcnt(0)
	global_atomic_add v1, v2, s[40:41]

.LBB0_2211:
	s_cmp_gt_i32 s44, 9
	s_cselect_b64 s[2:3], -1, 0
	s_cmp_lt_i32 s45, 10
	s_cselect_b64 s[4:5], -1, 0
	s_or_b64 s[2:3], s[2:3], s[4:5]
	s_and_b64 vcc, exec, s[2:3]
	s_cbranch_vccnz .LBB0_2341
	s_cmp_lt_u32 s70, 256
	s_cbranch_scc1 .Lprio_skip_9
	s_setprio 3

.LBB0_2287:
	s_setprio 0
	s_cmp_lt_i32 s45, 11
	s_cbranch_scc1 .LBB0_2341
	s_waitcnt vmcnt(0) lgkmcnt(0)
	s_barrier
	v_mbcnt_hi_u32_b32 v0, -1, v210
	v_cmp_eq_u32_e32 vcc, 0, v0
	s_and_b64 s[4:5], s[46:47], vcc
	s_and_saveexec_b64 s[2:3], s[4:5]
	s_cbranch_execz .Lfb9_join
	v_mov_b32_e32 v0, 0x24400
	ds_read_b32 v1, v0
	ds_read_b32 v2, v0 offset:4
	ds_read_b32 v3, v0 offset:8
	s_waitcnt lgkmcnt(0)
	v_readfirstlane_b32 s4, v1
	v_readfirstlane_b32 s5, v2
	v_readfirstlane_b32 s6, v3
	s_add_u32 s7, s6, 1
	v_mov_b32_e32 v4, s7
	ds_write_b32 v0, v4 offset:8
	s_mul_i32 s8, s7, s4
	s_mul_i32 s9, s7, s5
	s_lshl_b32 s10, s23, 7
	s_add_u32 s10, s10, 0x3600
	v_mov_b32_e32 v1, s10
	v_mov_b32_e32 v2, 1
	global_atomic_add v3, v1, v2, s[40:41] sc0
	s_waitcnt vmcnt(0)
	v_readfirstlane_b32 s11, v3
	s_add_u32 s11, s11, 1
	v_mov_b32_e32 v1, 0x3e00
	s_cmp_lg_u32 s11, s8
	s_cbranch_scc1 .Lfb9_spin
	buffer_wbl2 sc1
	s_waitcnt vmcnt(0)
	global_atomic_add v1, v2, s[40:41]

.LBB0_2401:
	s_cmp_gt_i32 s44, 11
	s_cselect_b64 s[2:3], -1, 0
	s_cmp_lt_i32 s45, 12
	s_cselect_b64 s[4:5], -1, 0
	s_or_b64 s[2:3], s[2:3], s[4:5]
	s_and_b64 vcc, exec, s[2:3]
	s_cbranch_vccnz .LBB0_3907
	s_cmp_lt_u32 s70, 256
	s_cbranch_scc1 .Lprio_skip_11
	s_setprio 3

.Lip11_done:
.LBB0_3853:
	s_setprio 0
	s_cmp_lt_i32 s45, 13
	s_cbranch_scc1 .LBB0_3907
	s_waitcnt vmcnt(0) lgkmcnt(0)
	s_barrier
	v_mbcnt_hi_u32_b32 v0, -1, v210
	v_cmp_eq_u32_e32 vcc, 0, v0
	s_and_b64 s[4:5], s[46:47], vcc
	s_and_saveexec_b64 s[2:3], s[4:5]
	s_cbranch_execz .Lfb11_join
	v_mov_b32_e32 v0, 0x24400
	ds_read_b32 v1, v0
	ds_read_b32 v2, v0 offset:4
	ds_read_b32 v3, v0 offset:8
	s_waitcnt lgkmcnt(0)
	v_readfirstlane_b32 s4, v1
	v_readfirstlane_b32 s5, v2
	v_readfirstlane_b32 s6, v3
	s_add_u32 s7, s6, 1
	v_mov_b32_e32 v4, s7
	ds_write_b32 v0, v4 offset:8
	s_mul_i32 s8, s7, s4
	s_mul_i32 s9, s7, s5
	s_lshl_b32 s10, s23, 7
	s_add_u32 s10, s10, 0x3600
	v_mov_b32_e32 v1, s10
	v_mov_b32_e32 v2, 1
	global_atomic_add v3, v1, v2, s[40:41] sc0
	s_waitcnt vmcnt(0)
	v_readfirstlane_b32 s11, v3
	s_add_u32 s11, s11, 1
	v_mov_b32_e32 v1, 0x3e00
	s_cmp_lg_u32 s11, s8
	s_cbranch_scc1 .Lfb11_spin
	buffer_wbl2 sc1
	s_waitcnt vmcnt(0)
	global_atomic_add v1, v2, s[40:41]

.LBB0_4470:
	s_cmp_gt_i32 s44, 16
	s_cselect_b64 s[2:3], -1, 0
	s_cmp_lt_i32 s45, 17
	s_cselect_b64 s[4:5], -1, 0
	s_or_b64 s[2:3], s[2:3], s[4:5]
	s_and_b64 vcc, exec, s[2:3]
	s_cbranch_vccnz .LBB0_4600
	s_cmp_lt_u32 s70, 256
	s_cbranch_scc1 .Lprio_skip_16
	s_setprio 3

.LBB0_4546:
	s_setprio 0
	s_cmp_lt_i32 s45, 18
	s_cbranch_scc1 .LBB0_4600
	s_waitcnt vmcnt(0) lgkmcnt(0)
	s_barrier
	v_mbcnt_hi_u32_b32 v0, -1, v210
	v_cmp_eq_u32_e32 vcc, 0, v0
	s_and_b64 s[4:5], s[46:47], vcc
	s_and_saveexec_b64 s[2:3], s[4:5]
	s_cbranch_execz .Lfb16_join
	v_mov_b32_e32 v0, 0x24400
	ds_read_b32 v1, v0
	ds_read_b32 v2, v0 offset:4
	ds_read_b32 v3, v0 offset:8
	s_waitcnt lgkmcnt(0)
	v_readfirstlane_b32 s4, v1
	v_readfirstlane_b32 s5, v2
	v_readfirstlane_b32 s6, v3
	s_add_u32 s7, s6, 1
	v_mov_b32_e32 v4, s7
	ds_write_b32 v0, v4 offset:8
	s_mul_i32 s8, s7, s4
	s_mul_i32 s9, s7, s5
	s_lshl_b32 s10, s23, 7
	s_add_u32 s10, s10, 0x3600
	v_mov_b32_e32 v1, s10
	v_mov_b32_e32 v2, 1
	global_atomic_add v3, v1, v2, s[40:41] sc0
	s_waitcnt vmcnt(0)
	v_readfirstlane_b32 s11, v3
	s_add_u32 s11, s11, 1
	v_mov_b32_e32 v1, 0x3e00
	s_cmp_lg_u32 s11, s8
	s_cbranch_scc1 .Lfb16_spin
	buffer_wbl2 sc1
	s_waitcnt vmcnt(0)
	global_atomic_add v1, v2, s[40:41]

.LBB0_4660:
	s_cmp_gt_i32 s44, 18
	s_cselect_b64 s[2:3], -1, 0
	s_cmp_lt_i32 s45, 19
	s_cselect_b64 s[4:5], -1, 0
	s_or_b64 s[2:3], s[2:3], s[4:5]
	s_and_b64 vcc, exec, s[2:3]
	s_cbranch_vccnz .LBB0_5230
	s_cmp_lt_u32 s70, 256
	s_cbranch_scc1 .Lprio_skip_18
	s_setprio 3

.LBB0_5176:
	s_setprio 0
	s_cmp_lt_i32 s45, 20
	s_cbranch_scc1 .LBB0_5230
	s_waitcnt vmcnt(0) lgkmcnt(0)
	s_barrier
	v_mbcnt_hi_u32_b32 v0, -1, v210
	v_cmp_eq_u32_e32 vcc, 0, v0
	s_and_b64 s[4:5], s[46:47], vcc
	s_and_saveexec_b64 s[2:3], s[4:5]
	s_cbranch_execz .Lfb18_join
	v_mov_b32_e32 v0, 0x24400
	ds_read_b32 v1, v0
	ds_read_b32 v2, v0 offset:4
	ds_read_b32 v3, v0 offset:8
	s_waitcnt lgkmcnt(0)
	v_readfirstlane_b32 s4, v1
	v_readfirstlane_b32 s5, v2
	v_readfirstlane_b32 s6, v3
	s_add_u32 s7, s6, 1
	v_mov_b32_e32 v4, s7
	ds_write_b32 v0, v4 offset:8
	s_mul_i32 s8, s7, s4
	s_mul_i32 s9, s7, s5
	s_lshl_b32 s10, s23, 7
	s_add_u32 s10, s10, 0x3600
	v_mov_b32_e32 v1, s10
	v_mov_b32_e32 v2, 1
	global_atomic_add v3, v1, v2, s[40:41] sc0
	s_waitcnt vmcnt(0)
	v_readfirstlane_b32 s11, v3
	s_add_u32 s11, s11, 1
	v_mov_b32_e32 v1, 0x3e00
	s_cmp_lg_u32 s11, s8
	s_cbranch_scc1 .Lfb18_spin
	buffer_wbl2 sc1
	s_waitcnt vmcnt(0)
	global_atomic_add v1, v2, s[40:41]

.LBB0_5230:
	s_cmp_gt_i32 s44, 19
	s_waitcnt lgkmcnt(0)
	s_cselect_b64 s[2:3], -1, 0
	s_cmp_lt_i32 s45, 20
	s_cselect_b64 s[4:5], -1, 0
	s_or_b64 s[2:3], s[2:3], s[4:5]
	s_and_b64 vcc, exec, s[2:3]
	s_cbranch_vccnz .LBB0_5559
	s_cmp_lt_u32 s70, 256
	s_cbranch_scc1 .Lprio_skip_19
	s_setprio 3

.Lmq19k_done:
.LBB0_5505:
	s_setprio 0
	s_cmp_lt_i32 s45, 21
	s_cbranch_scc1 .LBB0_5559
	s_waitcnt vmcnt(0) lgkmcnt(0)
	s_barrier
	v_mbcnt_hi_u32_b32 v0, -1, v210
	v_cmp_eq_u32_e32 vcc, 0, v0
	s_and_b64 s[4:5], s[46:47], vcc
	s_and_saveexec_b64 s[2:3], s[4:5]
	s_cbranch_execz .Lfb19_join
	v_mov_b32_e32 v0, 0x24400
	ds_read_b32 v1, v0
	ds_read_b32 v2, v0 offset:4
	ds_read_b32 v3, v0 offset:8
	s_waitcnt lgkmcnt(0)
	v_readfirstlane_b32 s4, v1
	v_readfirstlane_b32 s5, v2
	v_readfirstlane_b32 s6, v3
	s_add_u32 s7, s6, 1
	v_mov_b32_e32 v4, s7
	ds_write_b32 v0, v4 offset:8
	s_mul_i32 s8, s7, s4
	s_mul_i32 s9, s7, s5
	s_lshl_b32 s10, s23, 7
	s_add_u32 s10, s10, 0x3600
	v_mov_b32_e32 v1, s10
	v_mov_b32_e32 v2, 1
	global_atomic_add v3, v1, v2, s[40:41] sc0
	s_waitcnt vmcnt(0)
	v_readfirstlane_b32 s11, v3
	s_add_u32 s11, s11, 1
	v_mov_b32_e32 v1, 0x3e00
	s_cmp_lg_u32 s11, s8
	s_cbranch_scc1 .Lfb19_spin
	buffer_wbl2 sc1
	s_waitcnt vmcnt(0)
	global_atomic_add v1, v2, s[40:41]

.LBB0_5632:
	s_cmp_gt_i32 s44, 21
	s_cselect_b64 s[2:3], -1, 0
	s_cmp_lt_i32 s45, 22
	s_cselect_b64 s[4:5], -1, 0
	s_or_b64 s[2:3], s[2:3], s[4:5]
	s_and_b64 vcc, exec, s[2:3]
	s_cbranch_vccnz .LBB0_5762
	s_cmp_lt_u32 s70, 256
	s_cbranch_scc1 .Lprio_skip_21
	s_setprio 3

.LBB0_5708:
	s_setprio 0
	s_cmp_lt_i32 s45, 23
	s_cbranch_scc1 .LBB0_5762
	s_waitcnt vmcnt(0) lgkmcnt(0)
	s_barrier
	v_mbcnt_hi_u32_b32 v0, -1, v210
	v_cmp_eq_u32_e32 vcc, 0, v0
	s_and_b64 s[4:5], s[46:47], vcc
	s_and_saveexec_b64 s[2:3], s[4:5]
	s_cbranch_execz .Lfb21_join
	v_mov_b32_e32 v0, 0x24400
	ds_read_b32 v1, v0
	ds_read_b32 v2, v0 offset:4
	ds_read_b32 v3, v0 offset:8
	s_waitcnt lgkmcnt(0)
	v_readfirstlane_b32 s4, v1
	v_readfirstlane_b32 s5, v2
	v_readfirstlane_b32 s6, v3
	s_add_u32 s7, s6, 1
	v_mov_b32_e32 v4, s7
	ds_write_b32 v0, v4 offset:8
	s_mul_i32 s8, s7, s4
	s_mul_i32 s9, s7, s5
	s_lshl_b32 s10, s23, 7
	s_add_u32 s10, s10, 0x3600
	v_mov_b32_e32 v1, s10
	v_mov_b32_e32 v2, 1
	global_atomic_add v3, v1, v2, s[40:41] sc0
	s_waitcnt vmcnt(0)
	v_readfirstlane_b32 s11, v3
	s_add_u32 s11, s11, 1
	v_mov_b32_e32 v1, 0x3e00
	s_cmp_lg_u32 s11, s8
	s_cbranch_scc1 .Lfb21_spin
	buffer_wbl2 sc1
	s_waitcnt vmcnt(0)
	global_atomic_add v1, v2, s[40:41]
